# in-proj n-tile table variant: the class with two heavy q/k tiles gets the two cheapest (V) tiles
# speedup vs baseline: 1.0057x; 1.0057x over previous
; DI void inproj_phase(const Params& p, int l, char* smem) {
;     ...
;     for (int it = 0;; ++it) {
;         int mtile, nt;
;         if (xmap) {
;             if (it >= 4 || xj >= 63) break;
;             mtile = 9 * xcd + (xj % 9); nt = 7 * it + (xj / 9);
;         } else {
;             const int tile = blockIdx.x + it * gridDim.x;
;             if (tile >= MT * NT) break;
;             mtile = tile / NT; nt = tile % NT;
;         }
;         const int n0 = nt * 128;
.LBB0_192:
	s_mov_b64 s[4:5], 0
	s_cbranch_execz .LBB0_191
	s_cmp_lt_u32 s98, 4
	v_readlane_b32 s8, v255, 26
	s_cselect_b64 s[6:7], -1, 0
	v_readlane_b32 s9, v255, 27
	s_and_b64 s[6:7], s[8:9], s[6:7]
	s_and_b64 vcc, exec, s[6:7]
	s_cbranch_vccz .LBB0_195
	v_readlane_b32 s9, v254, 20
	v_readlane_b32 s50, v254, 19
	s_mov_b32 s6, 0x3020100
	s_mov_b32 s7, 0xb0a09
	s_cmp_eq_u32 s98, 1
	s_cselect_b32 s6, 0x12111008, s6
	s_cselect_b32 s7, 0x151413, s7
	s_cmp_eq_u32 s98, 2
	s_cselect_b32 s6, 0x17160c04, s6
	s_cselect_b32 s7, 0x1a0f18, s7
	s_cmp_eq_u32 s98, 3
	s_cselect_b32 s6, 0xd070605, s6
	s_cselect_b32 s7, 0x1b190e, s7
	s_lshl_b32 s9, s9, 3
	s_lshr_b64 s[6:7], s[6:7], s9
	s_and_b32 s99, s6, 0xff
	s_mov_b64 s[4:5], -1
